# tile-boundary peel on G1 only (plus hyena wait fixes and nyquist rewrite)
# speedup vs baseline: 1.0170x; 1.0170x over previous
.LBB0_337:
	s_add_u32 s6, s56, 0x8000000
	s_addc_u32 s7, s57, 0
	s_lshl_b32 s8, s8, 5
	s_and_b32 s17, s8, 0x60
	s_mov_b64 s[8:9], 0x80
	s_add_i32 m0, s34, 0x18000
	v_lshl_add_u64 v[8:9], v[8:9], 0, s[8:9]
	s_lshl_b32 s16, s1, 13
	s_waitcnt vmcnt(4)
	s_barrier
	global_load_lds_dwordx4 v[8:9], off
	v_lshl_add_u64 v[6:7], v[6:7], 0, s[8:9]
	s_add_i32 m0, s34, 0x1a000
	s_add_i32 s62, s34, 0x8000
	s_add_i32 s63, s34, 0xa000
	global_load_lds_dwordx4 v[6:7], off
	v_lshl_add_u64 v[4:5], v[4:5], 0, s[8:9]
	s_mov_b32 m0, s62
	s_add_u32 s10, s46, 0x80080
	global_load_lds_dwordx4 v[4:5], off
	v_lshl_add_u64 v[2:3], v[2:3], 0, s[8:9]
	s_mov_b32 m0, s63
	s_addc_u32 s11, s47, 0
	global_load_lds_dwordx4 v[2:3], off
	s_add_i32 m0, s34, 0x1c000
	v_lshl_add_u64 v[2:3], s[10:11], 0, v[132:133]
	global_load_lds_dwordx4 v[2:3], off
	v_lshl_add_u64 v[2:3], s[10:11], 0, v[136:137]
	s_add_i32 m0, s34, 0x1e000
	v_lshlrev_b32_e32 v4, 12, v152
	global_load_lds_dwordx4 v[2:3], off
	v_lshlrev_b32_e32 v3, 2, v1
	v_lshl_or_b32 v2, v1, 6, v155
	v_and_b32_e32 v3, 32, v3
	v_bitop3_b32 v2, v2, s16, v3 bitop3:0xde
	v_lshlrev_b32_e32 v3, 9, v151
	v_and_b32_e32 v3, 0x70000, v3
	v_or3_b32 v3, v150, v3, v4
	v_add_u32_e32 v138, v3, v147
	v_lshlrev_b32_e32 v3, 5, v153
	s_waitcnt vmcnt(6)
	v_and_b32_e32 v3, 0x70000, v3
	v_lshl_or_b32 v158, s17, 7, v156
	v_or3_b32 v3, v150, v3, v4
	s_add_i32 s65, 0, 0x10000
	s_add_i32 s66, 0, 0x14000
	s_sext_i32_i16 s71, s0
	v_lshl_or_b32 v157, s1, 6, v1
	s_ashr_i32 s64, s28, 31
	v_or_b32_e32 v159, s17, v154
	v_mov_b32_e32 v139, v133
	v_add_u32_e32 v140, v3, v147
	v_mov_b32_e32 v141, v133
	v_mov_b64_e32 v[142:143], 0x800
	v_mov_b64_e32 v[144:145], 0x7ff
	v_add_u32_e32 v160, s65, v158
	v_add_u32_e32 v161, 0, v2
	v_add_u32_e32 v162, s66, v158
	s_mov_b64 s[10:11], 0x800000
	s_mov_b32 s67, 0x800000
	s_mov_b64 s[16:17], 0x900000
	s_mov_b32 s68, 0x900000
	s_mov_b64 s[18:19], 0xa00000
	s_mov_b32 s69, 0xa00000
	s_mov_b64 s[24:25], 0xb00000
	s_mov_b32 s70, 0xb00000
	s_barrier
	s_mov_b32 s99, 0

.LBB0_344:
	s_ashr_i32 s37, s36, 31
	v_cmp_lt_i64_e32 vcc, s[38:39], v[142:143]
	s_lshl_b64 s[38:39], s[36:37], 20
	s_add_u32 s38, s30, s38
	s_addc_u32 s39, s31, s39
	s_and_b64 s[40:41], vcc, exec
	s_cselect_b32 s37, s39, s45
	s_cselect_b32 s72, s38, s44
	s_ashr_i32 s27, s26, 31
	s_lshl_b64 s[40:41], s[26:27], 20
	s_add_u32 s40, s56, s40
	s_addc_u32 s41, s57, s41
	s_and_b64 s[50:51], vcc, exec
	s_cselect_b32 s27, s41, s47
	s_cselect_b32 s73, s40, s46
	s_add_u32 s44, s44, 0x80080
	s_addc_u32 s45, s45, 0
	s_add_u32 s74, s46, 0x100
	v_mov_b32_e32 v2, 0
	s_addc_u32 s75, s47, 0
	s_mov_b32 s76, -2
	v_mov_b32_e32 v3, v2
	v_mov_b32_e32 v4, v2
	v_mov_b32_e32 v5, v2
	v_mov_b32_e32 v6, v2
	v_mov_b32_e32 v7, v2
	v_mov_b32_e32 v8, v2
	v_mov_b32_e32 v9, v2
	v_mov_b32_e32 v10, v2
	v_mov_b32_e32 v11, v2
	v_mov_b32_e32 v12, v2
	v_mov_b32_e32 v13, v2
	v_mov_b32_e32 v18, v2
	v_mov_b32_e32 v19, v2
	v_mov_b32_e32 v20, v2
	v_mov_b32_e32 v21, v2
	v_mov_b32_e32 v26, v2
	v_mov_b32_e32 v27, v2
	v_mov_b32_e32 v28, v2
	v_mov_b32_e32 v29, v2
	v_mov_b32_e32 v34, v2
	v_mov_b32_e32 v35, v2
	v_mov_b32_e32 v36, v2
	v_mov_b32_e32 v37, v2
	v_mov_b32_e32 v42, v2
	v_mov_b32_e32 v43, v2
	v_mov_b32_e32 v44, v2
	v_mov_b32_e32 v45, v2
	v_mov_b32_e32 v50, v2
	v_mov_b32_e32 v51, v2
	v_mov_b32_e32 v52, v2
	v_mov_b32_e32 v53, v2
	v_mov_b32_e32 v14, v2
	v_mov_b32_e32 v15, v2
	v_mov_b32_e32 v16, v2
	v_mov_b32_e32 v17, v2
	v_mov_b32_e32 v22, v2
	v_mov_b32_e32 v23, v2
	v_mov_b32_e32 v24, v2
	v_mov_b32_e32 v25, v2
	v_mov_b32_e32 v30, v2
	v_mov_b32_e32 v31, v2
	v_mov_b32_e32 v32, v2
	v_mov_b32_e32 v33, v2
	v_mov_b32_e32 v38, v2
	v_mov_b32_e32 v39, v2
	v_mov_b32_e32 v40, v2
	v_mov_b32_e32 v41, v2
	v_mov_b32_e32 v46, v2
	v_mov_b32_e32 v47, v2
	v_mov_b32_e32 v48, v2
	v_mov_b32_e32 v49, v2
	v_mov_b32_e32 v54, v2
	v_mov_b32_e32 v55, v2
	v_mov_b32_e32 v56, v2
	v_mov_b32_e32 v57, v2
	v_mov_b32_e32 v58, v2
	v_mov_b32_e32 v59, v2
	v_mov_b32_e32 v60, v2
	v_mov_b32_e32 v61, v2
	v_mov_b32_e32 v62, v2
	v_mov_b32_e32 v63, v2
	v_mov_b32_e32 v64, v2
	v_mov_b32_e32 v65, v2
	v_mov_b32_e32 v66, v2
	v_mov_b32_e32 v67, v2
	v_mov_b32_e32 v68, v2
	v_mov_b32_e32 v69, v2
	v_mov_b32_e32 v70, v2
	v_mov_b32_e32 v71, v2
	v_mov_b32_e32 v72, v2
	v_mov_b32_e32 v73, v2
	v_mov_b32_e32 v78, v2
	v_mov_b32_e32 v79, v2
	v_mov_b32_e32 v80, v2
	v_mov_b32_e32 v81, v2
	v_mov_b32_e32 v86, v2
	v_mov_b32_e32 v87, v2
	v_mov_b32_e32 v88, v2
	v_mov_b32_e32 v89, v2
	v_mov_b32_e32 v94, v2
	v_mov_b32_e32 v95, v2
	v_mov_b32_e32 v96, v2
	v_mov_b32_e32 v97, v2
	v_mov_b32_e32 v102, v2
	v_mov_b32_e32 v103, v2
	v_mov_b32_e32 v104, v2
	v_mov_b32_e32 v105, v2
	v_mov_b32_e32 v110, v2
	v_mov_b32_e32 v111, v2
	v_mov_b32_e32 v112, v2
	v_mov_b32_e32 v113, v2
	v_mov_b32_e32 v118, v2
	v_mov_b32_e32 v119, v2
	v_mov_b32_e32 v120, v2
	v_mov_b32_e32 v121, v2
	v_mov_b32_e32 v74, v2
	v_mov_b32_e32 v75, v2
	v_mov_b32_e32 v76, v2
	v_mov_b32_e32 v77, v2
	v_mov_b32_e32 v82, v2
	v_mov_b32_e32 v83, v2
	v_mov_b32_e32 v84, v2
	v_mov_b32_e32 v85, v2
	v_mov_b32_e32 v90, v2
	v_mov_b32_e32 v91, v2
	v_mov_b32_e32 v92, v2
	v_mov_b32_e32 v93, v2
	v_mov_b32_e32 v98, v2
	v_mov_b32_e32 v99, v2
	v_mov_b32_e32 v100, v2
	v_mov_b32_e32 v101, v2
	v_mov_b32_e32 v106, v2
	v_mov_b32_e32 v107, v2
	v_mov_b32_e32 v108, v2
	v_mov_b32_e32 v109, v2
	v_mov_b32_e32 v114, v2
	v_mov_b32_e32 v115, v2
	v_mov_b32_e32 v116, v2
	v_mov_b32_e32 v117, v2
	v_mov_b32_e32 v122, v2
	v_mov_b32_e32 v123, v2
	v_mov_b32_e32 v124, v2
	v_mov_b32_e32 v125, v2
	v_mov_b32_e32 v126, v2
	v_mov_b32_e32 v127, v2
	v_mov_b32_e32 v128, v2
	v_mov_b32_e32 v129, v2
	s_cmp_eq_u32 s99, 0
	s_cbranch_scc1 .LBB0_345
	ds_read_b128 v[164:167], v160
	ds_read_b128 v[168:171], v160 offset:1024
	ds_read_b128 v[172:175], v160 offset:2048
	ds_read_b128 v[176:179], v160 offset:3072
	s_add_u32 s46, s44, 0xfff80080
	s_addc_u32 s47, s45, -1
	s_cmp_eq_u32 s76, 28
	s_cselect_b32 s51, s37, s47
	s_cselect_b32 s50, s72, s46
	s_cselect_b32 s47, s27, s75
	s_cselect_b32 s46, s73, s74
	v_lshl_add_u64 v[148:149], s[44:45], 0, v[138:139]
	s_add_i32 m0, s34, 0xc000
	ds_read_b128 v[180:183], v161
	ds_read_b128 v[184:187], v161 offset:1024
	ds_read_b128 v[188:191], v161 offset:2048
	ds_read_b128 v[192:195], v161 offset:3072
	ds_read_b128 v[196:199], v161 offset:4096
	ds_read_b128 v[204:207], v161 offset:5120
	ds_read_b128 v[208:211], v161 offset:6144
	ds_read_b128 v[212:215], v161 offset:7168
	v_lshl_add_u64 v[148:149], s[44:45], 0, v[140:141]
	s_add_i32 m0, s34, 0xe000
	s_nop 0
	s_waitcnt lgkmcnt(8)
	s_barrier
	s_waitcnt lgkmcnt(0)
	s_setprio 1
	s_waitcnt lgkmcnt(0)
	v_mfma_f32_16x16x32_bf16 v[126:129], v[164:167], v[180:183], v[126:129]
	v_mfma_f32_16x16x32_bf16 v[122:125], v[172:175], v[180:183], v[122:125]
	v_mfma_f32_16x16x32_bf16 v[114:117], v[164:167], v[188:191], v[114:117]
	v_mfma_f32_16x16x32_bf16 v[106:109], v[172:175], v[188:191], v[106:109]
	v_mfma_f32_16x16x32_bf16 v[98:101], v[164:167], v[196:199], v[98:101]
	v_mfma_f32_16x16x32_bf16 v[90:93], v[172:175], v[196:199], v[90:93]
	v_mfma_f32_16x16x32_bf16 v[82:85], v[164:167], v[208:211], v[82:85]
	v_mfma_f32_16x16x32_bf16 v[74:77], v[172:175], v[208:211], v[74:77]
	v_mfma_f32_16x16x32_bf16 v[126:129], v[168:171], v[184:187], v[126:129]
	v_mfma_f32_16x16x32_bf16 v[122:125], v[176:179], v[184:187], v[122:125]
	v_mfma_f32_16x16x32_bf16 v[114:117], v[168:171], v[192:195], v[114:117]
	v_mfma_f32_16x16x32_bf16 v[106:109], v[176:179], v[192:195], v[106:109]
	v_mfma_f32_16x16x32_bf16 v[98:101], v[168:171], v[204:207], v[98:101]
	v_mfma_f32_16x16x32_bf16 v[90:93], v[176:179], v[204:207], v[90:93]
	v_mfma_f32_16x16x32_bf16 v[82:85], v[168:171], v[212:215], v[82:85]
	v_mfma_f32_16x16x32_bf16 v[74:77], v[176:179], v[212:215], v[74:77]
	s_setprio 0
	s_barrier
	s_add_i32 s77, s65, s33
	v_lshl_add_u64 v[148:149], s[46:47], 0, v[132:133]
	s_mov_b32 m0, s77
	ds_read_b128 v[216:219], v162
	ds_read_b128 v[220:223], v162 offset:1024
	ds_read_b128 v[224:227], v162 offset:2048
	ds_read_b128 v[228:231], v162 offset:3072
	global_load_lds_dwordx4 v[148:149], off
	v_lshl_add_u64 v[232:233], s[46:47], 0, v[136:137]
	s_add_i32 m0, s77, 0x2000
	s_nop 0
	global_load_lds_dwordx4 v[232:233], off
	s_barrier
	s_waitcnt lgkmcnt(0)
	s_setprio 1
	s_waitcnt lgkmcnt(0)
	v_mfma_f32_16x16x32_bf16 v[118:121], v[216:219], v[180:183], v[118:121]
	v_mfma_f32_16x16x32_bf16 v[110:113], v[224:227], v[180:183], v[110:113]
	v_mfma_f32_16x16x32_bf16 v[102:105], v[216:219], v[188:191], v[102:105]
	v_mfma_f32_16x16x32_bf16 v[94:97], v[224:227], v[188:191], v[94:97]
	v_mfma_f32_16x16x32_bf16 v[86:89], v[216:219], v[196:199], v[86:89]
	v_mfma_f32_16x16x32_bf16 v[78:81], v[224:227], v[196:199], v[78:81]
	v_mfma_f32_16x16x32_bf16 v[70:73], v[216:219], v[208:211], v[70:73]
	v_mfma_f32_16x16x32_bf16 v[66:69], v[224:227], v[208:211], v[66:69]
	v_mfma_f32_16x16x32_bf16 v[118:121], v[220:223], v[184:187], v[118:121]
	v_mfma_f32_16x16x32_bf16 v[110:113], v[228:231], v[184:187], v[110:113]
	v_mfma_f32_16x16x32_bf16 v[102:105], v[220:223], v[192:195], v[102:105]
	v_mfma_f32_16x16x32_bf16 v[94:97], v[228:231], v[192:195], v[94:97]
	v_mfma_f32_16x16x32_bf16 v[86:89], v[220:223], v[204:207], v[86:89]
	v_mfma_f32_16x16x32_bf16 v[78:81], v[228:231], v[204:207], v[78:81]
	v_mfma_f32_16x16x32_bf16 v[70:73], v[220:223], v[212:215], v[70:73]
	v_mfma_f32_16x16x32_bf16 v[66:69], v[228:231], v[212:215], v[66:69]
	s_setprio 0
	s_mov_b32 m0, s34
	v_lshl_add_u64 v[234:235], s[50:51], 0, v[130:131]
	s_barrier
	ds_read_b128 v[180:183], v161 offset:16384
	ds_read_b128 v[184:187], v161 offset:17408
	ds_read_b128 v[188:191], v161 offset:18432
	ds_read_b128 v[192:195], v161 offset:19456
	ds_read_b128 v[196:199], v161 offset:20480
	ds_read_b128 v[204:207], v161 offset:21504
	ds_read_b128 v[208:211], v161 offset:22528
	ds_read_b128 v[212:215], v161 offset:23552
	global_load_lds_dwordx4 v[234:235], off
	v_lshl_add_u64 v[236:237], s[50:51], 0, v[134:135]
	s_mov_b32 m0, s35
	s_nop 0
	global_load_lds_dwordx4 v[236:237], off
	s_barrier
	s_waitcnt lgkmcnt(0)
	s_setprio 1
	s_waitcnt lgkmcnt(0)
	v_mfma_f32_16x16x32_bf16 v[62:65], v[164:167], v[180:183], v[62:65]
	v_mfma_f32_16x16x32_bf16 v[58:61], v[172:175], v[180:183], v[58:61]
	v_mfma_f32_16x16x32_bf16 v[54:57], v[164:167], v[188:191], v[54:57]
	v_mfma_f32_16x16x32_bf16 v[46:49], v[172:175], v[188:191], v[46:49]
	v_mfma_f32_16x16x32_bf16 v[38:41], v[164:167], v[196:199], v[38:41]
	v_mfma_f32_16x16x32_bf16 v[30:33], v[172:175], v[196:199], v[30:33]
	v_mfma_f32_16x16x32_bf16 v[22:25], v[164:167], v[208:211], v[22:25]
	v_mfma_f32_16x16x32_bf16 v[14:17], v[172:175], v[208:211], v[14:17]
	v_mfma_f32_16x16x32_bf16 v[62:65], v[168:171], v[184:187], v[62:65]
	v_mfma_f32_16x16x32_bf16 v[58:61], v[176:179], v[184:187], v[58:61]
	v_mfma_f32_16x16x32_bf16 v[54:57], v[168:171], v[192:195], v[54:57]
	v_mfma_f32_16x16x32_bf16 v[46:49], v[176:179], v[192:195], v[46:49]
	v_mfma_f32_16x16x32_bf16 v[38:41], v[168:171], v[204:207], v[38:41]
	v_mfma_f32_16x16x32_bf16 v[30:33], v[176:179], v[204:207], v[30:33]
	v_mfma_f32_16x16x32_bf16 v[22:25], v[168:171], v[212:215], v[22:25]
	v_mfma_f32_16x16x32_bf16 v[14:17], v[176:179], v[212:215], v[14:17]
	s_setprio 0
	s_barrier
	s_add_u32 s78, s46, 0x80000
	s_addc_u32 s79, s47, 0
	s_add_i32 s77, s66, s33
	v_lshl_add_u64 v[164:165], s[78:79], 0, v[132:133]
	s_mov_b32 m0, s77
	s_nop 0
	global_load_lds_dwordx4 v[164:165], off
	v_lshl_add_u64 v[164:165], s[78:79], 0, v[136:137]
	s_add_i32 m0, s77, 0x2000
	s_nop 0
	global_load_lds_dwordx4 v[164:165], off
	s_waitcnt vmcnt(22)
	s_barrier
	s_setprio 1
	v_mfma_f32_16x16x32_bf16 v[50:53], v[216:219], v[180:183], v[50:53]
	v_mfma_f32_16x16x32_bf16 v[42:45], v[224:227], v[180:183], v[42:45]
	v_mfma_f32_16x16x32_bf16 v[34:37], v[216:219], v[188:191], v[34:37]
	v_mfma_f32_16x16x32_bf16 v[26:29], v[224:227], v[188:191], v[26:29]
	v_mfma_f32_16x16x32_bf16 v[18:21], v[216:219], v[196:199], v[18:21]
	v_mfma_f32_16x16x32_bf16 v[10:13], v[224:227], v[196:199], v[10:13]
	v_mfma_f32_16x16x32_bf16 v[6:9], v[216:219], v[208:211], v[6:9]
	v_mfma_f32_16x16x32_bf16 v[2:5], v[224:227], v[208:211], v[2:5]
	v_mfma_f32_16x16x32_bf16 v[50:53], v[220:223], v[184:187], v[50:53]
	v_mfma_f32_16x16x32_bf16 v[42:45], v[228:231], v[184:187], v[42:45]
	v_mfma_f32_16x16x32_bf16 v[34:37], v[220:223], v[192:195], v[34:37]
	v_mfma_f32_16x16x32_bf16 v[26:29], v[228:231], v[192:195], v[26:29]
	v_mfma_f32_16x16x32_bf16 v[18:21], v[220:223], v[204:207], v[18:21]
	v_mfma_f32_16x16x32_bf16 v[10:13], v[228:231], v[204:207], v[10:13]
	v_mfma_f32_16x16x32_bf16 v[6:9], v[220:223], v[212:215], v[6:9]
	v_mfma_f32_16x16x32_bf16 v[2:5], v[228:231], v[212:215], v[2:5]
	s_setprio 0
	s_add_i32 s77, 0, 0x18000
	v_add_u32_e32 v163, s77, v158
	s_barrier
	s_branch .Ltb_mid_g1

.Ltb_mid_g1:
	ds_read_b128 v[164:167], v163
	ds_read_b128 v[168:171], v163 offset:1024
	ds_read_b128 v[172:175], v163 offset:2048
	ds_read_b128 v[176:179], v163 offset:3072
	s_add_u32 s50, s50, 0x80000
	s_addc_u32 s51, s51, 0
	s_mov_b32 m0, s43
	v_lshl_add_u64 v[216:217], s[50:51], 0, v[130:131]
	ds_read_b128 v[180:183], v161 offset:32768
	ds_read_b128 v[184:187], v161 offset:33792
	ds_read_b128 v[188:191], v161 offset:34816
	ds_read_b128 v[192:195], v161 offset:35840
	ds_read_b128 v[196:199], v161 offset:36864
	ds_read_b128 v[204:207], v161 offset:37888
	ds_read_b128 v[208:211], v161 offset:38912
	ds_read_b128 v[212:215], v161 offset:39936
	global_load_lds_dwordx4 v[216:217], off
	v_lshl_add_u64 v[216:217], s[50:51], 0, v[134:135]
	s_mov_b32 m0, s60
	s_nop 0
	global_load_lds_dwordx4 v[216:217], off
	s_waitcnt lgkmcnt(8)
	s_barrier
	s_waitcnt lgkmcnt(0)
	s_setprio 1
	s_waitcnt lgkmcnt(0)
	v_mfma_f32_16x16x32_bf16 v[126:129], v[164:167], v[180:183], v[126:129]
	v_mfma_f32_16x16x32_bf16 v[122:125], v[172:175], v[180:183], v[122:125]
	v_mfma_f32_16x16x32_bf16 v[114:117], v[164:167], v[188:191], v[114:117]
	v_mfma_f32_16x16x32_bf16 v[106:109], v[172:175], v[188:191], v[106:109]
	v_mfma_f32_16x16x32_bf16 v[98:101], v[164:167], v[196:199], v[98:101]
	v_mfma_f32_16x16x32_bf16 v[90:93], v[172:175], v[196:199], v[90:93]
	v_mfma_f32_16x16x32_bf16 v[82:85], v[164:167], v[208:211], v[82:85]
	v_mfma_f32_16x16x32_bf16 v[74:77], v[172:175], v[208:211], v[74:77]
	v_mfma_f32_16x16x32_bf16 v[126:129], v[168:171], v[184:187], v[126:129]
	v_mfma_f32_16x16x32_bf16 v[122:125], v[176:179], v[184:187], v[122:125]
	v_mfma_f32_16x16x32_bf16 v[114:117], v[168:171], v[192:195], v[114:117]
	v_mfma_f32_16x16x32_bf16 v[106:109], v[176:179], v[192:195], v[106:109]
	v_mfma_f32_16x16x32_bf16 v[98:101], v[168:171], v[204:207], v[98:101]
	v_mfma_f32_16x16x32_bf16 v[90:93], v[176:179], v[204:207], v[90:93]
	v_mfma_f32_16x16x32_bf16 v[82:85], v[168:171], v[212:215], v[82:85]
	v_mfma_f32_16x16x32_bf16 v[74:77], v[176:179], v[212:215], v[74:77]
	s_setprio 0
	s_barrier
	s_add_i32 s50, 0, 0x1c000
	s_add_i32 s51, s77, s33
	v_add_u32_e32 v163, s50, v158
	v_lshl_add_u64 v[148:149], v[148:149], 0, s[8:9]
	s_mov_b32 m0, s51
	ds_read_b128 v[216:219], v163
	ds_read_b128 v[220:223], v163 offset:1024
	ds_read_b128 v[224:227], v163 offset:2048
	ds_read_b128 v[228:231], v163 offset:3072
	global_load_lds_dwordx4 v[148:149], off
	v_lshl_add_u64 v[148:149], v[232:233], 0, s[8:9]
	s_add_i32 m0, s51, 0x2000
	s_nop 0
	global_load_lds_dwordx4 v[148:149], off
	s_barrier
	s_waitcnt lgkmcnt(0)
	s_setprio 1
	s_waitcnt lgkmcnt(0)
	v_mfma_f32_16x16x32_bf16 v[118:121], v[216:219], v[180:183], v[118:121]
	v_mfma_f32_16x16x32_bf16 v[110:113], v[224:227], v[180:183], v[110:113]
	v_mfma_f32_16x16x32_bf16 v[102:105], v[216:219], v[188:191], v[102:105]
	v_mfma_f32_16x16x32_bf16 v[94:97], v[224:227], v[188:191], v[94:97]
	v_mfma_f32_16x16x32_bf16 v[86:89], v[216:219], v[196:199], v[86:89]
	v_mfma_f32_16x16x32_bf16 v[78:81], v[224:227], v[196:199], v[78:81]
	v_mfma_f32_16x16x32_bf16 v[70:73], v[216:219], v[208:211], v[70:73]
	v_mfma_f32_16x16x32_bf16 v[66:69], v[224:227], v[208:211], v[66:69]
	v_mfma_f32_16x16x32_bf16 v[118:121], v[220:223], v[184:187], v[118:121]
	v_mfma_f32_16x16x32_bf16 v[110:113], v[228:231], v[184:187], v[110:113]
	v_mfma_f32_16x16x32_bf16 v[102:105], v[220:223], v[192:195], v[102:105]
	v_mfma_f32_16x16x32_bf16 v[94:97], v[228:231], v[192:195], v[94:97]
	v_mfma_f32_16x16x32_bf16 v[86:89], v[220:223], v[204:207], v[86:89]
	v_mfma_f32_16x16x32_bf16 v[78:81], v[228:231], v[204:207], v[78:81]
	v_mfma_f32_16x16x32_bf16 v[70:73], v[220:223], v[212:215], v[70:73]
	v_mfma_f32_16x16x32_bf16 v[66:69], v[228:231], v[212:215], v[66:69]
	s_setprio 0
	s_mov_b32 m0, s62
	v_lshl_add_u64 v[148:149], v[234:235], 0, s[8:9]
	s_barrier
	ds_read_b128 v[180:183], v161 offset:49152
	ds_read_b128 v[184:187], v161 offset:50176
	ds_read_b128 v[188:191], v161 offset:51200
	ds_read_b128 v[192:195], v161 offset:52224
	ds_read_b128 v[196:199], v161 offset:53248
	ds_read_b128 v[204:207], v161 offset:54272
	ds_read_b128 v[208:211], v161 offset:55296
	ds_read_b128 v[212:215], v161 offset:56320
	global_load_lds_dwordx4 v[148:149], off
	v_lshl_add_u64 v[148:149], v[236:237], 0, s[8:9]
	s_mov_b32 m0, s63
	s_nop 0
	global_load_lds_dwordx4 v[148:149], off
	s_barrier
	s_waitcnt lgkmcnt(0)
	s_setprio 1
	s_waitcnt lgkmcnt(0)
	v_mfma_f32_16x16x32_bf16 v[62:65], v[164:167], v[180:183], v[62:65]
	v_mfma_f32_16x16x32_bf16 v[58:61], v[172:175], v[180:183], v[58:61]
	v_mfma_f32_16x16x32_bf16 v[54:57], v[164:167], v[188:191], v[54:57]
	v_mfma_f32_16x16x32_bf16 v[46:49], v[172:175], v[188:191], v[46:49]
	v_mfma_f32_16x16x32_bf16 v[38:41], v[164:167], v[196:199], v[38:41]
	v_mfma_f32_16x16x32_bf16 v[30:33], v[172:175], v[196:199], v[30:33]
	v_mfma_f32_16x16x32_bf16 v[22:25], v[164:167], v[208:211], v[22:25]
	v_mfma_f32_16x16x32_bf16 v[14:17], v[172:175], v[208:211], v[14:17]
	v_mfma_f32_16x16x32_bf16 v[62:65], v[168:171], v[184:187], v[62:65]
	v_mfma_f32_16x16x32_bf16 v[58:61], v[176:179], v[184:187], v[58:61]
	v_mfma_f32_16x16x32_bf16 v[54:57], v[168:171], v[192:195], v[54:57]
	v_mfma_f32_16x16x32_bf16 v[46:49], v[176:179], v[192:195], v[46:49]
	v_mfma_f32_16x16x32_bf16 v[38:41], v[168:171], v[204:207], v[38:41]
	v_mfma_f32_16x16x32_bf16 v[30:33], v[176:179], v[204:207], v[30:33]
	v_mfma_f32_16x16x32_bf16 v[22:25], v[168:171], v[212:215], v[22:25]
	v_mfma_f32_16x16x32_bf16 v[14:17], v[176:179], v[212:215], v[14:17]
	s_setprio 0
	s_barrier
	s_add_u32 s46, s46, 0x80080
	s_addc_u32 s47, s47, 0
	s_add_i32 s50, s50, s33
	v_lshl_add_u64 v[148:149], s[46:47], 0, v[132:133]
	s_mov_b32 m0, s50
	s_nop 0
	global_load_lds_dwordx4 v[148:149], off
	v_lshl_add_u64 v[148:149], s[46:47], 0, v[136:137]
	s_add_i32 m0, s50, 0x2000
	s_nop 0
	global_load_lds_dwordx4 v[148:149], off
	s_waitcnt vmcnt(6)
	s_barrier
	s_setprio 1
	v_mfma_f32_16x16x32_bf16 v[50:53], v[216:219], v[180:183], v[50:53]
	v_mfma_f32_16x16x32_bf16 v[42:45], v[224:227], v[180:183], v[42:45]
	v_mfma_f32_16x16x32_bf16 v[34:37], v[216:219], v[188:191], v[34:37]
	v_mfma_f32_16x16x32_bf16 v[26:29], v[224:227], v[188:191], v[26:29]
	v_mfma_f32_16x16x32_bf16 v[18:21], v[216:219], v[196:199], v[18:21]
	v_mfma_f32_16x16x32_bf16 v[10:13], v[224:227], v[196:199], v[10:13]
	v_mfma_f32_16x16x32_bf16 v[6:9], v[216:219], v[208:211], v[6:9]
	v_mfma_f32_16x16x32_bf16 v[2:5], v[224:227], v[208:211], v[2:5]
	v_mfma_f32_16x16x32_bf16 v[50:53], v[220:223], v[184:187], v[50:53]
	v_mfma_f32_16x16x32_bf16 v[42:45], v[228:231], v[184:187], v[42:45]
	v_mfma_f32_16x16x32_bf16 v[34:37], v[220:223], v[192:195], v[34:37]
	v_mfma_f32_16x16x32_bf16 v[26:29], v[228:231], v[192:195], v[26:29]
	v_mfma_f32_16x16x32_bf16 v[18:21], v[220:223], v[204:207], v[18:21]
	v_mfma_f32_16x16x32_bf16 v[10:13], v[228:231], v[204:207], v[10:13]
	v_mfma_f32_16x16x32_bf16 v[6:9], v[220:223], v[212:215], v[6:9]
	v_mfma_f32_16x16x32_bf16 v[2:5], v[228:231], v[212:215], v[2:5]
	s_setprio 0
	s_add_i32 s76, s76, 2
	s_add_u32 s44, s44, 0x100
	s_addc_u32 s45, s45, 0
	s_add_u32 s74, s74, 0x100
	s_addc_u32 s75, s75, 0
	s_cmp_gt_u32 s76, 29
	s_barrier
	s_cbranch_scc0 .LBB0_345
	s_add_u32 s100, s72, 0x80080
	s_addc_u32 s101, s37, 0
	v_lshl_add_u64 v[148:149], s[100:101], 0, v[138:139]
	s_add_i32 m0, s34, 0xc000
	s_nop 0
	global_load_lds_dwordx4 v[148:149], off
	v_lshl_add_u64 v[148:149], s[100:101], 0, v[140:141]
	s_add_i32 m0, s34, 0xe000
	s_nop 0
	global_load_lds_dwordx4 v[148:149], off
	s_mov_b32 s99, 1
	v_lshl_add_u32 v164, s42, 8, v157
	v_lshl_or_b32 v148, s71, 8, v159
	v_ashrrev_i32_e32 v165, 31, v164
	v_ashrrev_i32_e32 v149, 31, v148
	v_lshlrev_b64 v[166:167], 16, v[164:165]
	v_lshl_add_u64 v[166:167], s[6:7], 0, v[166:167]
	v_lshlrev_b64 v[168:169], 1, v[148:149]
	v_lshl_add_u64 v[148:149], v[166:167], 0, v[168:169]
	v_cvt_pk_bf16_f32 v126, v126, v127
	v_cvt_pk_bf16_f32 v127, v128, v129
	v_cvt_pk_bf16_f32 v128, v122, v123
	v_cvt_pk_bf16_f32 v129, v124, v125
	global_store_dwordx4 v[148:149], v[126:129], off
	v_cvt_pk_bf16_f32 v118, v118, v119
	v_cvt_pk_bf16_f32 v119, v120, v121
	v_cvt_pk_bf16_f32 v120, v110, v111
	v_or_b32_e32 v110, 16, v164
	v_ashrrev_i32_e32 v111, 31, v110
	v_lshlrev_b64 v[110:111], 16, v[110:111]
	v_lshl_add_u64 v[110:111], s[6:7], 0, v[110:111]
	v_cvt_pk_bf16_f32 v121, v112, v113
	global_store_dwordx4 v[148:149], v[118:121], off offset:256
	s_mov_b32 s71, s26
	s_mov_b32 s42, s36
	v_lshl_add_u64 v[118:119], v[110:111], 0, v[168:169]
	v_cvt_pk_bf16_f32 v110, v114, v115
	v_cvt_pk_bf16_f32 v111, v116, v117
	v_cvt_pk_bf16_f32 v112, v106, v107
	v_cvt_pk_bf16_f32 v113, v108, v109
	global_store_dwordx4 v[118:119], v[110:113], off
	v_cvt_pk_bf16_f32 v102, v102, v103
	v_cvt_pk_bf16_f32 v103, v104, v105
	v_cvt_pk_bf16_f32 v104, v94, v95
	v_or_b32_e32 v94, 32, v164
	v_ashrrev_i32_e32 v95, 31, v94
	v_lshlrev_b64 v[94:95], 16, v[94:95]
	v_lshl_add_u64 v[94:95], s[6:7], 0, v[94:95]
	v_cvt_pk_bf16_f32 v105, v96, v97
	global_store_dwordx4 v[118:119], v[102:105], off offset:256
	s_mov_b64 s[46:47], s[40:41]
	s_mov_b64 s[44:45], s[38:39]
	v_lshl_add_u64 v[102:103], v[94:95], 0, v[168:169]
	v_cvt_pk_bf16_f32 v94, v98, v99
	v_cvt_pk_bf16_f32 v95, v100, v101
	v_cvt_pk_bf16_f32 v96, v90, v91
	v_cvt_pk_bf16_f32 v97, v92, v93
	global_store_dwordx4 v[102:103], v[94:97], off
	v_cvt_pk_bf16_f32 v86, v86, v87
	v_cvt_pk_bf16_f32 v87, v88, v89
	v_cvt_pk_bf16_f32 v88, v78, v79
	v_or_b32_e32 v78, 48, v164
	v_ashrrev_i32_e32 v79, 31, v78
	v_lshlrev_b64 v[78:79], 16, v[78:79]
	v_lshl_add_u64 v[78:79], s[6:7], 0, v[78:79]
	v_cvt_pk_bf16_f32 v89, v80, v81
	global_store_dwordx4 v[102:103], v[86:89], off offset:256
	s_nop 1
	v_lshl_add_u64 v[86:87], v[78:79], 0, v[168:169]
	v_cvt_pk_bf16_f32 v78, v82, v83
	v_cvt_pk_bf16_f32 v79, v84, v85
	v_cvt_pk_bf16_f32 v80, v74, v75
	v_cvt_pk_bf16_f32 v81, v76, v77
	global_store_dwordx4 v[86:87], v[78:81], off
	v_cvt_pk_bf16_f32 v70, v70, v71
	v_cvt_pk_bf16_f32 v71, v72, v73
	v_cvt_pk_bf16_f32 v72, v66, v67
	v_cvt_pk_bf16_f32 v73, v68, v69
	global_store_dwordx4 v[86:87], v[70:73], off offset:256
	v_cvt_pk_bf16_f32 v62, v62, v63
	v_cvt_pk_bf16_f32 v63, v64, v65
	v_cvt_pk_bf16_f32 v64, v58, v59
	v_add_co_u32_e32 v58, vcc, s67, v148
	v_lshl_add_u64 v[66:67], v[148:149], 0, s[10:11]
	s_nop 0
	v_addc_co_u32_e32 v59, vcc, 0, v149, vcc
	v_cvt_pk_bf16_f32 v65, v60, v61
	global_store_dwordx4 v[58:59], v[62:65], off
	v_cvt_pk_bf16_f32 v50, v50, v51
	v_cvt_pk_bf16_f32 v51, v52, v53
	v_cvt_pk_bf16_f32 v52, v42, v43
	v_cvt_pk_bf16_f32 v53, v44, v45
	global_store_dwordx4 v[66:67], v[50:53], off offset:256
	v_cvt_pk_bf16_f32 v42, v54, v55
	v_cvt_pk_bf16_f32 v43, v56, v57
	v_cvt_pk_bf16_f32 v44, v46, v47
	v_add_co_u32_e32 v46, vcc, s68, v148
	s_nop 0
	v_lshl_add_u64 v[50:51], v[148:149], 0, s[16:17]
	v_addc_co_u32_e32 v47, vcc, 0, v149, vcc
	v_cvt_pk_bf16_f32 v45, v48, v49
	global_store_dwordx4 v[46:47], v[42:45], off
	v_cvt_pk_bf16_f32 v34, v34, v35
	v_cvt_pk_bf16_f32 v35, v36, v37
	v_cvt_pk_bf16_f32 v36, v26, v27
	v_cvt_pk_bf16_f32 v37, v28, v29
	global_store_dwordx4 v[50:51], v[34:37], off offset:256
	v_cvt_pk_bf16_f32 v26, v38, v39
	v_cvt_pk_bf16_f32 v27, v40, v41
	v_cvt_pk_bf16_f32 v28, v30, v31
	v_add_co_u32_e32 v30, vcc, s69, v148
	s_nop 0
	v_lshl_add_u64 v[34:35], v[148:149], 0, s[18:19]
	v_addc_co_u32_e32 v31, vcc, 0, v149, vcc
	v_cvt_pk_bf16_f32 v29, v32, v33
	global_store_dwordx4 v[30:31], v[26:29], off
	v_cvt_pk_bf16_f32 v18, v18, v19
	v_cvt_pk_bf16_f32 v19, v20, v21
	v_cvt_pk_bf16_f32 v20, v10, v11
	v_cvt_pk_bf16_f32 v21, v12, v13
	global_store_dwordx4 v[34:35], v[18:21], off offset:256
	v_cvt_pk_bf16_f32 v10, v22, v23
	v_cvt_pk_bf16_f32 v11, v24, v25
	v_cvt_pk_bf16_f32 v12, v14, v15
	v_add_co_u32_e32 v14, vcc, s70, v148
	s_nop 0
	v_lshl_add_u64 v[18:19], v[148:149], 0, s[24:25]
	v_addc_co_u32_e32 v15, vcc, 0, v149, vcc
	s_and_b64 vcc, exec, s[0:1]
	v_cvt_pk_bf16_f32 v13, v16, v17
	global_store_dwordx4 v[14:15], v[10:13], off
	v_cvt_pk_bf16_f32 v6, v6, v7
	v_cvt_pk_bf16_f32 v7, v8, v9
	v_cvt_pk_bf16_f32 v8, v2, v3
	v_cvt_pk_bf16_f32 v9, v4, v5
	global_store_dwordx4 v[18:19], v[6:9], off offset:256
	s_cbranch_vccz .LBB0_338
	s_waitcnt vmcnt(0)
	s_cmpk_gt_u32 s3, 0xff
	s_cbranch_scc1 .LBB0_349
	s_barrier

.LBB0_717:
	s_cmp_gt_u32 s2, 47
	s_cbranch_scc1 .LBB0_723
	v_readlane_b32 s36, v244, 0
	v_readlane_b32 s37, v244, 1
	v_readfirstlane_b32 s4, v200
	v_and_b32_e32 v1, 63, v0
	v_mov_b32_e32 v3, 0
	v_lshlrev_b32_e32 v2, 2, v1
	s_lshr_b32 s0, s2, 2
	s_and_b32 s0, s0, 3
	s_and_b32 s1, s2, 3
	s_lshl_b32 s1, s1, 8
	s_lshl_b32 s3, s0, 19
	s_add_u32 s3, s3, s1
	s_lshl_b32 s5, s4, 15
	s_add_u32 s3, s3, s5
	s_add_u32 s3, s3, 0x1e7a0000
	s_add_u32 s8, s56, s3
	s_addc_u32 s9, s57, 0
	s_lshr_b32 s10, s2, 4
	s_lshl_b32 s11, s10, 12
	s_lshl_b32 s16, s0, 10
	s_add_u32 s11, s11, s16
	s_lshl_b32 s16, s4, 7
	s_add_u32 s11, s11, s16
	s_add_u32 s11, s11, 0x1e9a0000
	s_add_u32 s16, s56, s11
	s_addc_u32 s17, s57, 0
	global_load_dwordx4 v[4:7], v3, s[16:17]
	global_load_dwordx4 v[8:11], v3, s[16:17] offset:16
	global_load_dwordx4 v[12:15], v3, s[16:17] offset:32
	global_load_dwordx4 v[16:19], v3, s[16:17] offset:48
	global_load_dwordx4 v[20:23], v3, s[16:17] offset:64
	global_load_dwordx4 v[24:27], v3, s[16:17] offset:80
	global_load_dwordx4 v[28:31], v3, s[16:17] offset:96
	global_load_dwordx4 v[32:35], v3, s[16:17] offset:112
	global_load_dword v36, v2, s[8:9]
	global_load_dword v37, v2, s[8:9] offset:1024
	global_load_dword v38, v2, s[8:9] offset:2048
	global_load_dword v39, v2, s[8:9] offset:3072
	s_add_u32 s8, s8, 0x1000
	s_addc_u32 s9, s9, 0
	global_load_dword v40, v2, s[8:9]
	global_load_dword v41, v2, s[8:9] offset:1024
	global_load_dword v42, v2, s[8:9] offset:2048
	global_load_dword v43, v2, s[8:9] offset:3072
	s_add_u32 s8, s8, 0x1000
	s_addc_u32 s9, s9, 0
	global_load_dword v44, v2, s[8:9]
	global_load_dword v45, v2, s[8:9] offset:1024
	global_load_dword v46, v2, s[8:9] offset:2048
	global_load_dword v47, v2, s[8:9] offset:3072
	s_add_u32 s8, s8, 0x1000
	s_addc_u32 s9, s9, 0
	global_load_dword v48, v2, s[8:9]
	global_load_dword v49, v2, s[8:9] offset:1024
	global_load_dword v50, v2, s[8:9] offset:2048
	global_load_dword v51, v2, s[8:9] offset:3072
	s_add_u32 s8, s8, 0x1000
	s_addc_u32 s9, s9, 0
	global_load_dword v52, v2, s[8:9]
	global_load_dword v53, v2, s[8:9] offset:1024
	global_load_dword v54, v2, s[8:9] offset:2048
	global_load_dword v55, v2, s[8:9] offset:3072
	s_add_u32 s8, s8, 0x1000
	s_addc_u32 s9, s9, 0
	global_load_dword v56, v2, s[8:9]
	global_load_dword v57, v2, s[8:9] offset:1024
	global_load_dword v58, v2, s[8:9] offset:2048
	global_load_dword v59, v2, s[8:9] offset:3072
	s_add_u32 s8, s8, 0x1000
	s_addc_u32 s9, s9, 0
	global_load_dword v60, v2, s[8:9]
	global_load_dword v61, v2, s[8:9] offset:1024
	global_load_dword v62, v2, s[8:9] offset:2048
	global_load_dword v63, v2, s[8:9] offset:3072
	s_add_u32 s8, s8, 0x1000
	s_addc_u32 s9, s9, 0
	global_load_dword v64, v2, s[8:9]
	global_load_dword v65, v2, s[8:9] offset:1024
	global_load_dword v66, v2, s[8:9] offset:2048
	global_load_dword v67, v2, s[8:9] offset:3072
	s_and_b32 s0, s2, 15
	s_lshl_b32 s0, s0, 6
	v_add_u32_e32 v78, s0, v1
	v_lshlrev_b32_e32 v79, 2, v78
	global_load_dword v80, v79, s[36:37]
	v_lshl_add_u32 v69, s4, 8, v2
	s_waitcnt vmcnt(1)
	v_mul_f32_e32 v68, v4, v36
	v_fmac_f32_e32 v68, v5, v37
	v_fmac_f32_e32 v68, v6, v38
	v_fmac_f32_e32 v68, v7, v39
	v_fmac_f32_e32 v68, v8, v40
	v_fmac_f32_e32 v68, v9, v41
	v_fmac_f32_e32 v68, v10, v42
	v_fmac_f32_e32 v68, v11, v43
	v_fmac_f32_e32 v68, v12, v44
	v_fmac_f32_e32 v68, v13, v45
	v_fmac_f32_e32 v68, v14, v46
	v_fmac_f32_e32 v68, v15, v47
	v_fmac_f32_e32 v68, v16, v48
	v_fmac_f32_e32 v68, v17, v49
	v_fmac_f32_e32 v68, v18, v50
	v_fmac_f32_e32 v68, v19, v51
	v_fmac_f32_e32 v68, v20, v52
	v_fmac_f32_e32 v68, v21, v53
	v_fmac_f32_e32 v68, v22, v54
	v_fmac_f32_e32 v68, v23, v55
	v_fmac_f32_e32 v68, v24, v56
	v_fmac_f32_e32 v68, v25, v57
	v_fmac_f32_e32 v68, v26, v58
	v_fmac_f32_e32 v68, v27, v59
	v_fmac_f32_e32 v68, v28, v60
	v_fmac_f32_e32 v68, v29, v61
	v_fmac_f32_e32 v68, v30, v62
	v_fmac_f32_e32 v68, v31, v63
	v_fmac_f32_e32 v68, v32, v64
	v_fmac_f32_e32 v68, v33, v65
	v_fmac_f32_e32 v68, v34, v66
	v_fmac_f32_e32 v68, v35, v67
	s_barrier
	ds_write_b32 v69, v68
	s_waitcnt lgkmcnt(0)
	s_barrier
	s_cmp_lg_u32 s4, 0
	s_cbranch_scc1 .LBB0_723
	ds_read_b32 v70, v2
	ds_read_b32 v71, v2 offset:256
	ds_read_b32 v72, v2 offset:512
	ds_read_b32 v73, v2 offset:768
	ds_read_b32 v74, v2 offset:1024
	ds_read_b32 v75, v2 offset:1280
	ds_read_b32 v76, v2 offset:1536
	ds_read_b32 v77, v2 offset:1792
	s_mov_b32 s1, 0x3a3504f3
	s_mov_b32 s3, 0x3a000000
	s_lshl_b32 s0, s10, 24
	s_add_u32 s0, s0, 0x1800000
	s_cmp_eq_u32 s10, 0
	s_cselect_b32 s1, s3, s1
	s_cselect_b32 s0, 0x1000000, s0
	s_add_u32 s0, s0, 0x8000000
	s_add_u32 s8, s56, s0
	s_addc_u32 s9, s57, 0
	v_lshlrev_b32_e32 v82, 1, v78
	s_movk_i32 s3, 0x7fff
	s_waitcnt lgkmcnt(0)
	v_add_f32_e32 v70, v70, v71
	v_add_f32_e32 v72, v72, v73
	v_add_f32_e32 v74, v74, v75
	v_add_f32_e32 v76, v76, v77
	v_add_f32_e32 v70, v70, v72
	v_add_f32_e32 v74, v74, v76
	v_add_f32_e32 v70, v70, v74
	s_waitcnt vmcnt(0)
	v_fma_f32 v70, v70, s1, v80
	v_bfe_u32 v71, v70, 16, 1
	v_add3_u32 v71, v70, v71, s3
	global_store_short_d16_hi v82, v71, s[8:9]

	.amdhsa_kernel _Z4mega6Params
		.amdhsa_group_segment_fixed_size 0
		.amdhsa_private_segment_fixed_size 0
		.amdhsa_kernarg_size 448
		.amdhsa_user_sgpr_count 2
		.amdhsa_user_sgpr_dispatch_ptr 0
		.amdhsa_user_sgpr_queue_ptr 0
		.amdhsa_user_sgpr_kernarg_segment_ptr 1
		.amdhsa_user_sgpr_dispatch_id 0
		.amdhsa_user_sgpr_kernarg_preload_length 0
		.amdhsa_user_sgpr_kernarg_preload_offset 0
		.amdhsa_user_sgpr_private_segment_size 0
		.amdhsa_uses_dynamic_stack 0
		.amdhsa_enable_private_segment 0
		.amdhsa_system_sgpr_workgroup_id_x 1
		.amdhsa_system_sgpr_workgroup_id_y 0
		.amdhsa_system_sgpr_workgroup_id_z 0
		.amdhsa_system_sgpr_workgroup_info 0
		.amdhsa_system_vgpr_workitem_id 2
		.amdhsa_next_free_vgpr 245
		.amdhsa_next_free_sgpr 102
		.amdhsa_accum_offset 248
		.amdhsa_reserve_vcc 1
		.amdhsa_float_round_mode_32 0
		.amdhsa_float_round_mode_16_64 0
		.amdhsa_float_denorm_mode_32 3
		.amdhsa_float_denorm_mode_16_64 3
		.amdhsa_dx10_clamp 1
		.amdhsa_ieee_mode 1
		.amdhsa_fp16_overflow 0
		.amdhsa_tg_split 0
		.amdhsa_exception_fp_ieee_invalid_op 0
		.amdhsa_exception_fp_denorm_src 0
		.amdhsa_exception_fp_ieee_div_zero 0
		.amdhsa_exception_fp_ieee_overflow 0
		.amdhsa_exception_fp_ieee_underflow 0
		.amdhsa_exception_fp_ieee_inexact 0
		.amdhsa_exception_int_div_zero 0
	.end_amdhsa_kernel

amdhsa.kernels:
  - .agpr_count:     0
    .args:
      - .offset:         0
        .size:           192
        .value_kind:     by_value
      - .offset:         192
        .size:           4
        .value_kind:     hidden_block_count_x
      - .offset:         196
        .size:           4
        .value_kind:     hidden_block_count_y
      - .offset:         200
        .size:           4
        .value_kind:     hidden_block_count_z
      - .offset:         204
        .size:           2
        .value_kind:     hidden_group_size_x
      - .offset:         206
        .size:           2
        .value_kind:     hidden_group_size_y
      - .offset:         208
        .size:           2
        .value_kind:     hidden_group_size_z
      - .offset:         210
        .size:           2
        .value_kind:     hidden_remainder_x
      - .offset:         212
        .size:           2
        .value_kind:     hidden_remainder_y
      - .offset:         214
        .size:           2
        .value_kind:     hidden_remainder_z
      - .offset:         232
        .size:           8
        .value_kind:     hidden_global_offset_x
      - .offset:         240
        .size:           8
        .value_kind:     hidden_global_offset_y
      - .offset:         248
        .size:           8
        .value_kind:     hidden_global_offset_z
      - .offset:         256
        .size:           2
        .value_kind:     hidden_grid_dims
      - .offset:         280
        .size:           8
        .value_kind:     hidden_multigrid_sync_arg
      - .offset:         312
        .size:           4
        .value_kind:     hidden_dynamic_lds_size
    .group_segment_fixed_size: 0
    .kernarg_segment_align: 8
    .kernarg_segment_size: 448
    .language:       OpenCL C
    .language_version:
      - 2
      - 0
    .max_flat_workgroup_size: 512
    .name:           _Z4mega6Params
    .private_segment_fixed_size: 0
    .sgpr_count:     108
    .sgpr_spill_count: 18
    .symbol:         _Z4mega6Params.kd
    .uniform_work_group_size: 1
    .uses_dynamic_stack: false
    .vgpr_count:     245
    .vgpr_spill_count: 0
    .wavefront_size: 64
